# relu (fmaxf(x,0)) in FF1 epilogue, sample FF1 and indexer scores: the canonicalising v_max x,x in front of v_max 0,x dropped (spacing to SGPR writers and wide stores kept with s_nop)
# speedup vs baseline: 1.0249x; 1.0095x over previous
; __device__ __forceinline__ void select_group(unsigned char* ws, int r0, const bf16_t* __restrict__ kib, int n, float* sc, SelPre& pre, int nr0, const bf16_t* __restrict__ nkib, int nn) {
;     ...
; #pragma unroll
;       for (int u = 0; u < 4; ++u) {
;         if (kb0 + 8 * u < nkb) {
;           const int key = (kb0 + 8 * u) * 32 + i;
;           f32x16 acc;
; #pragma unroll
;           for (int e = 0; e < 16; ++e) acc[e] = 0.f;
; #pragma unroll
;           for (int ks = 0; ks < 4; ++ks) acc = __builtin_amdgcn_mfma_f32_32x32x16_bf16(af[ks], bfr[u][ks], acc, 0, 0, 0);
; #pragma unroll
;           for (int jj = 0; jj < 4; ++jj) {
;             float sco = wv[jj][0] * fmaxf(acc[4 * jj], 0.f) + wv[jj][1] * fmaxf(acc[4 * jj + 1], 0.f) + wv[jj][2] * fmaxf(acc[4 * jj + 2], 0.f) +
;                         wv[jj][3] * fmaxf(acc[4 * jj + 3], 0.f);
;             sco += 0.0f;
;             sc[(2 * jj + kg) * 4096 + key] = sco;
;           }
;         }
;       }
.LBB0_2904:
	v_mov_b32_e32 v205, v244
	s_cmpk_gt_u32 s57, 0x100
	v_and_b32_e32 v114, 63, v205
	v_ashrrev_i32_e32 v206, 6, v205
	s_mov_b64 s[2:3], -1
	s_cbranch_scc0 .LBB0_2921
	s_lshr_b32 s10, s57, 5
	v_cmp_gt_i32_e32 vcc, s10, v206
	s_and_saveexec_b64 s[4:5], vcc
	s_cbranch_execz .LBB0_2932
	v_mfma_f32_32x32x16_bf16 v[0:15], v[18:21], v[50:53], 0
	v_and_b32_e32 v16, 31, v205
	v_lshlrev_b32_e32 v116, 2, v16
	v_lshlrev_b32_e32 v16, 9, v114
	v_and_b32_e32 v117, 0x4000, v16
	v_add3_u32 v16, 0, v116, v117
	v_lshlrev_b32_e32 v118, 7, v206
	v_add_u32_e32 v115, v16, v118
	v_mfma_f32_32x32x16_bf16 v[0:15], v[22:25], v[54:57], v[0:15]
	v_mfma_f32_32x32x16_bf16 v[0:15], v[26:29], v[58:61], v[0:15]
	v_mfma_f32_32x32x16_bf16 v[0:15], v[30:33], v[62:65], v[0:15]
	s_nop 11
	v_max_f32_e32 v1, 0, v1
	v_max_f32_e32 v5, 0, v5
	v_max_f32_e32 v0, 0, v0
	v_max_f32_e32 v4, 0, v4
	v_mul_f32_e32 v1, v35, v1
	v_mul_f32_e32 v5, v39, v5
	v_max_f32_e32 v2, 0, v2
	v_max_f32_e32 v6, 0, v6
	v_fmac_f32_e32 v1, v34, v0
	v_fmac_f32_e32 v5, v38, v4
	v_max_f32_e32 v3, 0, v3
	v_max_f32_e32 v7, 0, v7
	v_fmac_f32_e32 v1, v36, v2
	v_fmac_f32_e32 v5, v40, v6
	v_fmac_f32_e32 v1, v37, v3
	v_fmac_f32_e32 v5, v41, v7
	v_add_f32_e32 v0, 0, v1
	v_add_f32_e32 v1, 0, v5
	ds_write2st64_b32 v115, v0, v1 offset1:128
	s_nop 0
	s_nop 0
	v_max_f32_e32 v0, 0, v9
	v_max_f32_e32 v8, 0, v8
	v_mul_f32_e32 v0, v43, v0
	v_fmac_f32_e32 v0, v42, v8
	v_max_f32_e32 v1, 0, v10
	v_fmac_f32_e32 v0, v44, v1
	v_max_f32_e32 v1, 0, v11
	v_fmac_f32_e32 v0, v45, v1
	v_add_f32_e32 v0, 0, v0
	v_add_u32_e32 v1, 0x10000, v115
	ds_write_b32 v1, v0
	s_nop 0
	s_nop 0
	v_max_f32_e32 v1, 0, v13
	v_max_f32_e32 v0, 0, v12
	v_mul_f32_e32 v1, v47, v1
	v_fmac_f32_e32 v1, v46, v0
	v_max_f32_e32 v0, 0, v14
	v_fmac_f32_e32 v1, v48, v0
	v_max_f32_e32 v0, 0, v15
	v_fmac_f32_e32 v1, v49, v0
	v_add_f32_e32 v0, 0, v1
	v_add_u32_e32 v1, 0x18000, v115
	v_add_u32_e32 v115, 8, v206
	v_cmp_gt_i32_e32 vcc, s10, v115
	ds_write_b32 v1, v0
	s_and_saveexec_b64 s[2:3], vcc
	s_cbranch_execz .LBB0_2908
	v_mfma_f32_32x32x16_bf16 v[0:15], v[18:21], v[66:69], 0
	v_lshl_add_u32 v115, v115, 7, v16
	v_mfma_f32_32x32x16_bf16 v[0:15], v[22:25], v[78:81], v[0:15]
	v_mfma_f32_32x32x16_bf16 v[0:15], v[26:29], v[82:85], v[0:15]
	v_mfma_f32_32x32x16_bf16 v[0:15], v[30:33], v[86:89], v[0:15]
	s_nop 11
	v_max_f32_e32 v1, 0, v1
	v_max_f32_e32 v5, 0, v5
	v_max_f32_e32 v0, 0, v0
	v_max_f32_e32 v4, 0, v4
	v_mul_f32_e32 v1, v35, v1
	v_mul_f32_e32 v5, v39, v5
	v_max_f32_e32 v2, 0, v2
	v_max_f32_e32 v6, 0, v6
	v_fmac_f32_e32 v1, v34, v0
	v_fmac_f32_e32 v5, v38, v4
	v_max_f32_e32 v3, 0, v3
	v_max_f32_e32 v7, 0, v7
	v_fmac_f32_e32 v1, v36, v2
	v_fmac_f32_e32 v5, v40, v6
	v_max_f32_e32 v9, 0, v9
	v_fmac_f32_e32 v1, v37, v3
	v_fmac_f32_e32 v5, v41, v7
	v_max_f32_e32 v8, 0, v8
	v_mul_f32_e32 v9, v43, v9
	v_add_f32_e32 v0, 0, v1
	v_add_f32_e32 v1, 0, v5
	v_max_f32_e32 v10, 0, v10
	v_fmac_f32_e32 v9, v42, v8
	ds_write2st64_b32 v115, v0, v1 offset1:128
	s_nop 0
	v_fmac_f32_e32 v9, v44, v10
	v_max_f32_e32 v0, 0, v11
	v_fmac_f32_e32 v9, v45, v0
	v_add_f32_e32 v0, 0, v9
	v_add_u32_e32 v1, 0x10000, v115
	ds_write_b32 v1, v0
	s_nop 0
	s_nop 0
	v_max_f32_e32 v1, 0, v13
	v_max_f32_e32 v0, 0, v12
	v_mul_f32_e32 v1, v47, v1
	v_fmac_f32_e32 v1, v46, v0
	v_max_f32_e32 v0, 0, v14
	v_fmac_f32_e32 v1, v48, v0
	v_max_f32_e32 v0, 0, v15
	v_fmac_f32_e32 v1, v49, v0
	v_add_f32_e32 v0, 0, v1
	v_add_u32_e32 v1, 0x18000, v115
	ds_write_b32 v1, v0
.LBB0_2908:
	s_or_b64 exec, exec, s[2:3]
	v_add_u32_e32 v115, 16, v206
	v_cmp_gt_i32_e32 vcc, s10, v115
	s_and_saveexec_b64 s[2:3], vcc
	s_cbranch_execz .LBB0_2910
	v_mfma_f32_32x32x16_bf16 v[0:15], v[18:21], v[106:109], 0
	v_lshl_add_u32 v115, v115, 7, v16
	v_mfma_f32_32x32x16_bf16 v[0:15], v[22:25], v[110:113], v[0:15]
	v_mfma_f32_32x32x16_bf16 v[0:15], v[26:29], v[74:77], v[0:15]
	v_mfma_f32_32x32x16_bf16 v[0:15], v[30:33], v[70:73], v[0:15]
	s_nop 11
	v_max_f32_e32 v1, 0, v1
	v_max_f32_e32 v5, 0, v5
	v_max_f32_e32 v0, 0, v0
	v_max_f32_e32 v4, 0, v4
	v_mul_f32_e32 v1, v35, v1
	v_mul_f32_e32 v5, v39, v5
	v_max_f32_e32 v2, 0, v2
	v_max_f32_e32 v6, 0, v6
	v_fmac_f32_e32 v1, v34, v0
	v_fmac_f32_e32 v5, v38, v4
	v_max_f32_e32 v3, 0, v3
	v_max_f32_e32 v7, 0, v7
	v_fmac_f32_e32 v1, v36, v2
	v_fmac_f32_e32 v5, v40, v6
	v_max_f32_e32 v9, 0, v9
	v_fmac_f32_e32 v1, v37, v3
	v_fmac_f32_e32 v5, v41, v7
	v_max_f32_e32 v8, 0, v8
	v_mul_f32_e32 v9, v43, v9
	v_add_f32_e32 v0, 0, v1
	v_add_f32_e32 v1, 0, v5
	v_max_f32_e32 v10, 0, v10
	v_fmac_f32_e32 v9, v42, v8
	ds_write2st64_b32 v115, v0, v1 offset1:128
	s_nop 0
	v_fmac_f32_e32 v9, v44, v10
	v_max_f32_e32 v0, 0, v11
	v_fmac_f32_e32 v9, v45, v0
	v_add_f32_e32 v0, 0, v9
	v_add_u32_e32 v1, 0x10000, v115
	ds_write_b32 v1, v0
	s_nop 0
	s_nop 0
	v_max_f32_e32 v1, 0, v13
	v_max_f32_e32 v0, 0, v12
	v_mul_f32_e32 v1, v47, v1
	v_fmac_f32_e32 v1, v46, v0
	v_max_f32_e32 v0, 0, v14
	v_fmac_f32_e32 v1, v48, v0
	v_max_f32_e32 v0, 0, v15
	v_fmac_f32_e32 v1, v49, v0
	v_add_f32_e32 v0, 0, v1
	v_add_u32_e32 v1, 0x18000, v115
	ds_write_b32 v1, v0
.LBB0_2910:
	s_or_b64 exec, exec, s[2:3]
	v_add_u32_e32 v115, 24, v206
	v_cmp_gt_i32_e32 vcc, s10, v115
	s_and_saveexec_b64 s[2:3], vcc
	s_cbranch_execz .LBB0_2912
	v_mfma_f32_32x32x16_bf16 v[0:15], v[18:21], v[102:105], 0
	v_lshl_add_u32 v16, v115, 7, v16
	v_mfma_f32_32x32x16_bf16 v[0:15], v[22:25], v[98:101], v[0:15]
	v_mfma_f32_32x32x16_bf16 v[0:15], v[26:29], v[94:97], v[0:15]
	v_mfma_f32_32x32x16_bf16 v[0:15], v[30:33], v[90:93], v[0:15]
	s_nop 11
	v_max_f32_e32 v1, 0, v1
	v_max_f32_e32 v5, 0, v5
	v_max_f32_e32 v0, 0, v0
	v_max_f32_e32 v4, 0, v4
	v_mul_f32_e32 v1, v35, v1
	v_mul_f32_e32 v5, v39, v5
	v_max_f32_e32 v2, 0, v2
	v_max_f32_e32 v6, 0, v6
	v_fmac_f32_e32 v1, v34, v0
	v_fmac_f32_e32 v5, v38, v4
	v_max_f32_e32 v3, 0, v3
	v_max_f32_e32 v7, 0, v7
	v_fmac_f32_e32 v1, v36, v2
	v_fmac_f32_e32 v5, v40, v6
	v_max_f32_e32 v9, 0, v9
	v_fmac_f32_e32 v1, v37, v3
	v_fmac_f32_e32 v5, v41, v7
	v_max_f32_e32 v8, 0, v8
	v_mul_f32_e32 v9, v43, v9
	v_add_f32_e32 v0, 0, v1
	v_add_f32_e32 v1, 0, v5
	v_max_f32_e32 v10, 0, v10
	v_fmac_f32_e32 v9, v42, v8
	ds_write2st64_b32 v16, v0, v1 offset1:128
	s_nop 0
	v_fmac_f32_e32 v9, v44, v10
	v_max_f32_e32 v0, 0, v11
	v_fmac_f32_e32 v9, v45, v0
	v_add_f32_e32 v0, 0, v9
	v_add_u32_e32 v1, 0x10000, v16
	ds_write_b32 v1, v0
	s_nop 0
	s_nop 0
	v_max_f32_e32 v1, 0, v13
	v_max_f32_e32 v0, 0, v12
	v_mul_f32_e32 v1, v47, v1
	v_fmac_f32_e32 v1, v46, v0
	v_max_f32_e32 v0, 0, v14
	v_fmac_f32_e32 v1, v48, v0
	v_max_f32_e32 v0, 0, v15
	v_fmac_f32_e32 v1, v49, v0
	v_add_f32_e32 v0, 0, v1
	v_add_u32_e32 v1, 0x18000, v16
	ds_write_b32 v1, v0

; __device__ __forceinline__ void select_group(unsigned char* ws, int r0, const bf16_t* __restrict__ kib, int n, float* sc, SelPre& pre, int nr0, const bf16_t* __restrict__ nkib, int nn) {
;     ...
; #pragma unroll
;         for (int u = 0; u < 4; ++u) {
;           const int kbu = kb0 + 8 * u < nkb ? kb0 + 8 * u : kb0;
;           const bf16_t* krow = kib + (size_t)kbu * 2048 + lane * 8;
; #pragma unroll
;           for (int ks = 0; ks < 4; ++ks) bfr[u][ks] = *(const bf16x8*)(krow + ks * 512);
;         }
;       }
; #pragma unroll
;       for (int u = 0; u < 4; ++u) {
;         if (kb0 + 8 * u < nkb) {
;           const int key = (kb0 + 8 * u) * 32 + i;
;           f32x16 acc;
; #pragma unroll
;           for (int e = 0; e < 16; ++e) acc[e] = 0.f;
; #pragma unroll
;           for (int ks = 0; ks < 4; ++ks) acc = __builtin_amdgcn_mfma_f32_32x32x16_bf16(af[ks], bfr[u][ks], acc, 0, 0, 0);
; #pragma unroll
;           for (int jj = 0; jj < 4; ++jj) {
;             float sco = wv[jj][0] * fmaxf(acc[4 * jj], 0.f) + wv[jj][1] * fmaxf(acc[4 * jj + 1], 0.f) + wv[jj][2] * fmaxf(acc[4 * jj + 2], 0.f) +
;                         wv[jj][3] * fmaxf(acc[4 * jj + 3], 0.f);
;             sco += 0.0f;
;             sc[(2 * jj + kg) * 4096 + key] = sco;
;           }
;         }
;       }
.LBB0_2915:
	global_load_dwordx4 v[0:3], v[150:151], off offset:-3072
	global_load_dwordx4 v[116:119], v[150:151], off offset:-2048
	global_load_dwordx4 v[128:131], v[150:151], off offset:-1024
	global_load_dwordx4 v[154:157], v[150:151], off
	v_add_u32_e32 v4, 16, v115
	v_cmp_gt_i32_e64 s[0:1], s10, v4
	s_waitcnt vmcnt(6)
	v_add_u32_e32 v121, 24, v115
	v_cmp_gt_i32_e32 vcc, s10, v121
	v_cndmask_b32_e64 v120, v115, v4, s[0:1]
	v_add_u32_e32 v152, 8, v115
	v_cndmask_b32_e32 v122, v115, v121, vcc
	v_ashrrev_i32_e32 v121, 31, v120
	v_ashrrev_i32_e32 v123, 31, v122
	v_lshlrev_b64 v[120:121], 12, v[120:121]
	v_lshlrev_b64 v[122:123], 12, v[122:123]
	v_lshl_add_u64 v[120:121], v[148:149], 0, v[120:121]
	v_add_u32_e32 v153, 0xffff0000, v16
	v_cmp_gt_i32_e64 s[2:3], s10, v152
	v_add_u32_e32 v158, 0xffff8000, v16
	s_waitcnt vmcnt(3)
	v_mfma_f32_32x32x16_bf16 v[0:15], v[18:21], v[0:3], 0
	s_waitcnt vmcnt(2)
	v_mfma_f32_32x32x16_bf16 v[0:15], v[22:25], v[116:119], v[0:15]
	v_lshl_add_u64 v[116:117], v[148:149], 0, v[122:123]
	global_load_dwordx4 v[144:147], v[120:121], off
	global_load_dwordx4 v[140:143], v[120:121], off offset:1024
	global_load_dwordx4 v[136:139], v[120:121], off offset:2048
	global_load_dwordx4 v[132:135], v[120:121], off offset:3072
	global_load_dwordx4 v[124:127], v[116:117], off
	s_nop 0
	global_load_dwordx4 v[120:123], v[116:117], off offset:1024
	s_waitcnt vmcnt(7)
	v_mfma_f32_32x32x16_bf16 v[0:15], v[26:29], v[128:131], v[0:15]
	global_load_dwordx4 v[128:131], v[116:117], off offset:2048
	s_nop 0
	global_load_dwordx4 v[116:119], v[116:117], off offset:3072
	s_waitcnt vmcnt(8)
	v_mfma_f32_32x32x16_bf16 v[0:15], v[30:33], v[154:157], v[0:15]
	s_nop 11
	v_max_f32_e32 v1, 0, v1
	v_max_f32_e32 v0, 0, v0
	v_max_f32_e32 v5, 0, v5
	v_max_f32_e32 v9, 0, v9
	v_max_f32_e32 v13, 0, v13
	v_mul_f32_e32 v1, v35, v1
	v_max_f32_e32 v2, 0, v2
	v_max_f32_e32 v4, 0, v4
	v_max_f32_e32 v8, 0, v8
	v_max_f32_e32 v12, 0, v12
	v_mul_f32_e32 v5, v39, v5
	v_mul_f32_e32 v9, v43, v9
	v_mul_f32_e32 v13, v47, v13
	v_fmac_f32_e32 v1, v34, v0
	v_max_f32_e32 v3, 0, v3
	v_max_f32_e32 v6, 0, v6
	v_max_f32_e32 v10, 0, v10
	v_max_f32_e32 v14, 0, v14
	v_fmac_f32_e32 v5, v38, v4
	v_fmac_f32_e32 v9, v42, v8
	v_fmac_f32_e32 v13, v46, v12
	v_fmac_f32_e32 v1, v36, v2
	v_max_f32_e32 v7, 0, v7
	v_max_f32_e32 v11, 0, v11
	v_max_f32_e32 v15, 0, v15
	v_fmac_f32_e32 v5, v40, v6
	v_fmac_f32_e32 v9, v44, v10
	v_fmac_f32_e32 v13, v48, v14
	v_fmac_f32_e32 v1, v37, v3
	v_fmac_f32_e32 v5, v41, v7
	v_fmac_f32_e32 v9, v45, v11
	v_fmac_f32_e32 v13, v49, v15
	v_add_f32_e32 v0, 0, v1
	v_add_f32_e32 v1, 0, v5
	v_add_f32_e32 v2, 0, v9
	v_add_f32_e32 v3, 0, v13
	ds_write_b32 v153, v0
	ds_write_b32 v158, v1
	ds_write2st64_b32 v16, v2, v3 offset1:128
	s_and_saveexec_b64 s[8:9], s[2:3]
	s_cbranch_execz .LBB0_2918
	v_cndmask_b32_e64 v0, v115, v152, s[2:3]
	v_ashrrev_i32_e32 v1, 31, v0
	v_lshlrev_b64 v[0:1], 12, v[0:1]
	v_lshl_add_u64 v[156:157], v[148:149], 0, v[0:1]
	global_load_dwordx4 v[0:3], v[156:157], off
	global_load_dwordx4 v[152:155], v[156:157], off offset:1024
	s_waitcnt vmcnt(1)
	v_mfma_f32_32x32x16_bf16 v[0:15], v[18:21], v[0:3], 0
	s_waitcnt vmcnt(0)
	v_mfma_f32_32x32x16_bf16 v[0:15], v[22:25], v[152:155], v[0:15]
	global_load_dwordx4 v[152:155], v[156:157], off offset:2048
	s_waitcnt vmcnt(0)
	v_mfma_f32_32x32x16_bf16 v[0:15], v[26:29], v[152:155], v[0:15]
	global_load_dwordx4 v[152:155], v[156:157], off offset:3072
	v_add_u32_e32 v156, 0xffff0400, v16
	v_add_u32_e32 v157, 0xffff8400, v16
	s_waitcnt vmcnt(0)
	v_mfma_f32_32x32x16_bf16 v[0:15], v[30:33], v[152:155], v[0:15]
	s_nop 11
	v_max_f32_e32 v1, 0, v1
	v_max_f32_e32 v0, 0, v0
	v_max_f32_e32 v5, 0, v5
	v_max_f32_e32 v9, 0, v9
	v_max_f32_e32 v13, 0, v13
	v_mul_f32_e32 v1, v35, v1
	v_max_f32_e32 v2, 0, v2
	v_max_f32_e32 v4, 0, v4
	v_max_f32_e32 v8, 0, v8
	v_max_f32_e32 v12, 0, v12
	v_mul_f32_e32 v5, v39, v5
	v_mul_f32_e32 v9, v43, v9
	v_mul_f32_e32 v13, v47, v13
	v_fmac_f32_e32 v1, v34, v0
	v_max_f32_e32 v3, 0, v3
	v_max_f32_e32 v6, 0, v6
	v_max_f32_e32 v10, 0, v10
	v_max_f32_e32 v14, 0, v14
	v_fmac_f32_e32 v5, v38, v4
	v_fmac_f32_e32 v9, v42, v8
	v_fmac_f32_e32 v13, v46, v12
	v_fmac_f32_e32 v1, v36, v2
	v_max_f32_e32 v7, 0, v7
	v_max_f32_e32 v11, 0, v11
	v_max_f32_e32 v15, 0, v15
	v_fmac_f32_e32 v5, v40, v6
	v_fmac_f32_e32 v9, v44, v10
	v_fmac_f32_e32 v13, v48, v14
	v_fmac_f32_e32 v1, v37, v3
	v_fmac_f32_e32 v5, v41, v7
	v_fmac_f32_e32 v9, v45, v11
	v_fmac_f32_e32 v13, v49, v15
	v_add_f32_e32 v0, 0, v1
	v_add_f32_e32 v1, 0, v5
	v_add_f32_e32 v2, 0, v9
	v_add_f32_e32 v3, 0, v13
	ds_write_b32 v156, v0
	ds_write_b32 v157, v1
	ds_write2st64_b32 v16, v2, v3 offset0:4 offset1:132
	s_or_b64 exec, exec, s[8:9]
	s_and_saveexec_b64 s[2:3], s[0:1]
	s_cbranch_execnz .LBB0_2919

; __device__ __forceinline__ void select_group(unsigned char* ws, int r0, const bf16_t* __restrict__ kib, int n, float* sc, SelPre& pre, int nr0, const bf16_t* __restrict__ nkib, int nn) {
;     ...
; #pragma unroll
;       for (int u = 0; u < 4; ++u) {
;         if (kb0 + 8 * u < nkb) {
;           const int key = (kb0 + 8 * u) * 32 + i;
;           f32x16 acc;
; #pragma unroll
;           for (int e = 0; e < 16; ++e) acc[e] = 0.f;
; #pragma unroll
;           for (int ks = 0; ks < 4; ++ks) acc = __builtin_amdgcn_mfma_f32_32x32x16_bf16(af[ks], bfr[u][ks], acc, 0, 0, 0);
; #pragma unroll
;           for (int jj = 0; jj < 4; ++jj) {
;             float sco = wv[jj][0] * fmaxf(acc[4 * jj], 0.f) + wv[jj][1] * fmaxf(acc[4 * jj + 1], 0.f) + wv[jj][2] * fmaxf(acc[4 * jj + 2], 0.f) +
;                         wv[jj][3] * fmaxf(acc[4 * jj + 3], 0.f);
;             sco += 0.0f;
;             sc[(2 * jj + kg) * 4096 + key] = sco;
;           }
;         }
;       }
.LBB0_2919:
	s_waitcnt vmcnt(7)
	v_mfma_f32_32x32x16_bf16 v[0:15], v[18:21], v[144:147], 0
	s_waitcnt vmcnt(6)
	v_mfma_f32_32x32x16_bf16 v[0:15], v[22:25], v[140:143], v[0:15]
	s_waitcnt vmcnt(5)
	v_mfma_f32_32x32x16_bf16 v[0:15], v[26:29], v[136:139], v[0:15]
	v_add_u32_e32 v136, 0xffff0800, v16
	v_add_u32_e32 v137, 0xffff8800, v16
	s_waitcnt vmcnt(4)
	v_mfma_f32_32x32x16_bf16 v[0:15], v[30:33], v[132:135], v[0:15]
	s_nop 11
	v_max_f32_e32 v1, 0, v1
	v_max_f32_e32 v5, 0, v5
	v_max_f32_e32 v0, 0, v0
	v_max_f32_e32 v4, 0, v4
	v_mul_f32_e32 v1, v35, v1
	v_mul_f32_e32 v5, v39, v5
	v_max_f32_e32 v2, 0, v2
	v_max_f32_e32 v6, 0, v6
	v_fmac_f32_e32 v1, v34, v0
	v_fmac_f32_e32 v5, v38, v4
	v_max_f32_e32 v3, 0, v3
	v_max_f32_e32 v7, 0, v7
	v_fmac_f32_e32 v1, v36, v2
	v_fmac_f32_e32 v5, v40, v6
	v_fmac_f32_e32 v1, v37, v3
	v_fmac_f32_e32 v5, v41, v7
	v_add_f32_e32 v0, 0, v1
	v_add_f32_e32 v1, 0, v5
	ds_write_b32 v136, v0
	ds_write_b32 v137, v1
	s_nop 0
	v_max_f32_e32 v2, 0, v13
	v_max_f32_e32 v9, 0, v9
	v_max_f32_e32 v1, 0, v12
	v_mul_f32_e32 v2, v47, v2
	v_max_f32_e32 v8, 0, v8
	v_mul_f32_e32 v9, v43, v9
	v_fmac_f32_e32 v2, v46, v1
	v_fmac_f32_e32 v9, v42, v8
	v_max_f32_e32 v0, 0, v10
	v_max_f32_e32 v1, 0, v14
	v_fmac_f32_e32 v9, v44, v0
	v_fmac_f32_e32 v2, v48, v1
	v_max_f32_e32 v0, 0, v11
	v_max_f32_e32 v1, 0, v15
	v_fmac_f32_e32 v9, v45, v0
	v_fmac_f32_e32 v2, v49, v1
	v_add_f32_e32 v0, 0, v9
	v_add_f32_e32 v1, 0, v2
	ds_write2st64_b32 v16, v0, v1 offset0:8 offset1:136
	s_or_b64 exec, exec, s[2:3]
	s_and_saveexec_b64 s[0:1], vcc
	s_cbranch_execz .LBB0_2914
.LBB0_2920:
	s_waitcnt vmcnt(3)
	v_mfma_f32_32x32x16_bf16 v[0:15], v[18:21], v[124:127], 0
	s_waitcnt vmcnt(2)
	v_mfma_f32_32x32x16_bf16 v[0:15], v[22:25], v[120:123], v[0:15]
	v_add_u32_e32 v120, 0xffff0c00, v16
	v_add_u32_e32 v121, 0xffff8c00, v16
	s_waitcnt vmcnt(1)
	v_mfma_f32_32x32x16_bf16 v[0:15], v[26:29], v[128:131], v[0:15]
	s_waitcnt vmcnt(0)
	v_mfma_f32_32x32x16_bf16 v[0:15], v[30:33], v[116:119], v[0:15]
	s_nop 11
	v_max_f32_e32 v1, 0, v1
	v_max_f32_e32 v5, 0, v5
	v_max_f32_e32 v0, 0, v0
	v_max_f32_e32 v4, 0, v4
	v_mul_f32_e32 v1, v35, v1
	v_mul_f32_e32 v5, v39, v5
	v_max_f32_e32 v2, 0, v2
	v_max_f32_e32 v6, 0, v6
	v_fmac_f32_e32 v1, v34, v0
	v_fmac_f32_e32 v5, v38, v4
	v_max_f32_e32 v3, 0, v3
	v_max_f32_e32 v7, 0, v7
	v_fmac_f32_e32 v1, v36, v2
	v_fmac_f32_e32 v5, v40, v6
	v_fmac_f32_e32 v1, v37, v3
	v_fmac_f32_e32 v5, v41, v7
	v_add_f32_e32 v0, 0, v1
	v_add_f32_e32 v1, 0, v5
	ds_write_b32 v120, v0
	ds_write_b32 v121, v1
	s_nop 0
	v_max_f32_e32 v2, 0, v13
	v_max_f32_e32 v9, 0, v9
	v_max_f32_e32 v1, 0, v12
	v_mul_f32_e32 v2, v47, v2
	v_max_f32_e32 v8, 0, v8
	v_mul_f32_e32 v9, v43, v9
	v_fmac_f32_e32 v2, v46, v1
	v_fmac_f32_e32 v9, v42, v8
	v_max_f32_e32 v0, 0, v10
	v_max_f32_e32 v1, 0, v14
	v_fmac_f32_e32 v9, v44, v0
	v_fmac_f32_e32 v2, v48, v1
	v_max_f32_e32 v0, 0, v11
	v_max_f32_e32 v1, 0, v15
	v_fmac_f32_e32 v9, v45, v0
	v_fmac_f32_e32 v2, v49, v1
	v_add_f32_e32 v0, 0, v9
	v_add_f32_e32 v1, 0, v2
	ds_write2st64_b32 v16, v0, v1 offset0:12 offset1:140
	s_branch .LBB0_2914

; __device__ __forceinline__ void tile32(const bf16_t* __restrict__ A, int lda, const bf16_t* __restrict__ Bt, int ldb, int K, int row0, int col0, int lane, f32x4 (&c)[2][2]) {
;   const int i = lane & 15, kg = lane >> 4;
;   const bf16_t* a0 = A + (size_t)(row0 + i) * lda + kg * 8;
;   const bf16_t* a1 = a0 + (size_t)16 * lda;
;   const bf16_t* b0 = Bt + (size_t)(col0 + i) * ldb + kg * 8;
;   const bf16_t* b1 = b0 + (size_t)16 * ldb;
; #pragma unroll 4
;   for (int k = 0; k < K; k += 32) {
;     const bf16x8 af0 = *(const bf16x8*)(a0 + k), af1 = *(const bf16x8*)(a1 + k), bf0 = *(const bf16x8*)(b0 + k), bf1 = *(const bf16x8*)(b1 + k);
;     c[0][0] = __builtin_amdgcn_mfma_f32_16x16x32_bf16(af0, bf0, c[0][0], 0, 0, 0);
;     c[0][1] = __builtin_amdgcn_mfma_f32_16x16x32_bf16(af0, bf1, c[0][1], 0, 0, 0);
;     c[1][0] = __builtin_amdgcn_mfma_f32_16x16x32_bf16(af1, bf0, c[1][0], 0, 0, 0);
;     c[1][1] = __builtin_amdgcn_mfma_f32_16x16x32_bf16(af1, bf1, c[1][1], 0, 0, 0);
;   }
; __device__ __forceinline__ void sample_ff1(unsigned char* ws, int l) {
;     ...
; #pragma unroll
;     for (int rb = 0; rb < 2; ++rb)
; #pragma unroll
;       for (int cc = 0; cc < 2; ++cc)
; #pragma unroll
;         for (int j = 0; j < 4; ++j) {
;           const float a = fmaxf(c[rb][cc][j], 0.f);
;           H[(size_t)(row0 + 16 * rb + (lane >> 4) * 4 + j) * LDH + col0 + 16 * cc + (lane & 15)] = (bf16_t)(cvt_pk_bf16(a * a, 0.f) & 0xffffu);
;         }
.LBB0_3788:
	v_lshl_add_u64 v[32:33], v[24:25], 0, v[20:21]
	v_lshl_add_u64 v[34:35], v[22:23], 0, v[20:21]
	s_mov_b32 s0, 0x39c0000
	s_mov_b32 s4, 0x1908000
	v_add_co_u32_e32 v44, vcc, s0, v32
	s_mov_b32 s0, 0x39c8000
	s_mov_b32 s2, 0x1900000
	v_add_co_u32_e64 v50, s[4:5], s4, v34
	v_add_co_u32_e64 v46, s[0:1], s0, v32
	v_add_co_u32_e64 v48, s[2:3], s2, v34
	v_addc_co_u32_e32 v45, vcc, 0, v33, vcc
	v_addc_co_u32_e64 v51, vcc, 0, v35, s[4:5]
	v_addc_co_u32_e64 v47, vcc, 0, v33, s[0:1]
	v_addc_co_u32_e64 v49, vcc, 0, v35, s[2:3]
	global_load_dwordx4 v[32:35], v[44:45], off
	global_load_dwordx4 v[36:39], v[48:49], off
	global_load_dwordx4 v[40:43], v[50:51], off
	s_addk_i32 s20, 0x80
	v_lshl_add_u64 v[22:23], v[22:23], 0, s[18:19]
	s_cmpk_lt_u32 s20, 0x3e0
	v_lshl_add_u64 v[24:25], v[24:25], 0, s[18:19]
	s_waitcnt vmcnt(1)
	v_mfma_f32_16x16x32_bf16 v[12:15], v[32:35], v[36:39], v[12:15]
	s_waitcnt vmcnt(0)
	v_mfma_f32_16x16x32_bf16 v[8:11], v[32:35], v[40:43], v[8:11]
	global_load_dwordx4 v[32:35], v[46:47], off
	s_waitcnt vmcnt(0)
	v_mfma_f32_16x16x32_bf16 v[4:7], v[32:35], v[36:39], v[4:7]
	global_load_dwordx4 v[36:39], v[44:45], off offset:64
	v_mfma_f32_16x16x32_bf16 v[0:3], v[32:35], v[40:43], v[0:3]
	global_load_dwordx4 v[32:35], v[48:49], off offset:64
	global_load_dwordx4 v[40:43], v[50:51], off offset:64
	s_waitcnt vmcnt(1)
	v_mfma_f32_16x16x32_bf16 v[12:15], v[36:39], v[32:35], v[12:15]
	s_waitcnt vmcnt(0)
	v_mfma_f32_16x16x32_bf16 v[8:11], v[36:39], v[40:43], v[8:11]
	global_load_dwordx4 v[36:39], v[46:47], off offset:64
	s_waitcnt vmcnt(0)
	v_mfma_f32_16x16x32_bf16 v[4:7], v[36:39], v[32:35], v[4:7]
	global_load_dwordx4 v[32:35], v[44:45], off offset:128
	v_mfma_f32_16x16x32_bf16 v[0:3], v[36:39], v[40:43], v[0:3]
	global_load_dwordx4 v[36:39], v[48:49], off offset:128
	global_load_dwordx4 v[40:43], v[50:51], off offset:128
	s_waitcnt vmcnt(1)
	v_mfma_f32_16x16x32_bf16 v[12:15], v[32:35], v[36:39], v[12:15]
	s_waitcnt vmcnt(0)
	v_mfma_f32_16x16x32_bf16 v[8:11], v[32:35], v[40:43], v[8:11]
	global_load_dwordx4 v[32:35], v[46:47], off offset:128
	s_waitcnt vmcnt(0)
	v_mfma_f32_16x16x32_bf16 v[4:7], v[32:35], v[36:39], v[4:7]
	global_load_dwordx4 v[36:39], v[44:45], off offset:192
	v_mfma_f32_16x16x32_bf16 v[0:3], v[32:35], v[40:43], v[0:3]
	global_load_dwordx4 v[32:35], v[48:49], off offset:192
	global_load_dwordx4 v[40:43], v[50:51], off offset:192
	s_waitcnt vmcnt(1)
	v_mfma_f32_16x16x32_bf16 v[12:15], v[36:39], v[32:35], v[12:15]
	s_waitcnt vmcnt(0)
	v_mfma_f32_16x16x32_bf16 v[8:11], v[36:39], v[40:43], v[8:11]
	global_load_dwordx4 v[36:39], v[46:47], off offset:192
	s_waitcnt vmcnt(0)
	v_mfma_f32_16x16x32_bf16 v[4:7], v[36:39], v[32:35], v[4:7]
	v_mfma_f32_16x16x32_bf16 v[0:3], v[36:39], v[40:43], v[0:3]
	s_cbranch_scc1 .LBB0_3788
	v_or_b32_e32 v31, v16, v28
	v_lshlrev_b32_e32 v16, 6, v26
	v_and_b32_e32 v16, 0x1fc0, v16
	v_max_f32_e32 v12, 0, v12
	v_lshl_add_u64 v[22:23], v[18:19], 0, v[16:17]
	v_mul_f32_e32 v12, v12, v12
	s_movk_i32 s2, 0x2080
	v_cvt_pk_bf16_f32 v12, v12, v17
	v_mad_i64_i32 v[24:25], s[0:1], v31, s2, v[22:23]
	global_store_short v[24:25], v12, off
	s_nop 0
	v_max_f32_e32 v12, 0, v13
	v_mul_f32_e32 v12, v12, v12
	v_cvt_pk_bf16_f32 v16, v12, v17
	v_or_b32_e32 v12, 1, v31
	v_mad_i64_i32 v[12:13], s[0:1], v12, s2, v[22:23]
	v_max_f32_e32 v14, 0, v14
	global_store_short v[12:13], v16, off
	v_mul_f32_e32 v14, v14, v14
	v_or_b32_e32 v16, 2, v31
	v_cvt_pk_bf16_f32 v14, v14, v17
	v_mad_i64_i32 v[32:33], s[0:1], v16, s2, v[22:23]
	global_store_short v[32:33], v14, off
	s_nop 0
	v_max_f32_e32 v14, 0, v15
	v_mul_f32_e32 v14, v14, v14
	s_nop 0
	v_cvt_pk_bf16_f32 v16, v14, v17
	v_or_b32_e32 v14, 3, v31
	v_max_f32_e32 v8, 0, v8
	v_mad_i64_i32 v[14:15], s[0:1], v14, s2, v[22:23]
	v_mul_f32_e32 v8, v8, v8
	global_store_short v[14:15], v16, off
	v_cvt_pk_bf16_f32 v8, v8, v17
	global_store_short v[24:25], v8, off offset:32
	s_nop 0
	v_max_f32_e32 v8, 0, v9
	v_mul_f32_e32 v8, v8, v8
	v_cvt_pk_bf16_f32 v8, v8, v17
	global_store_short v[12:13], v8, off offset:32
	s_nop 0
	v_max_f32_e32 v8, 0, v10
	v_mul_f32_e32 v8, v8, v8
	v_cvt_pk_bf16_f32 v8, v8, v17
	global_store_short v[32:33], v8, off offset:32
	s_nop 0
	v_max_f32_e32 v8, 0, v11
	v_mul_f32_e32 v8, v8, v8
	v_cvt_pk_bf16_f32 v8, v8, v17
	v_max_f32_e32 v4, 0, v4
	global_store_short v[14:15], v8, off offset:32
	v_or_b32_e32 v8, 16, v31
	v_mul_f32_e32 v4, v4, v4
	v_cvt_pk_bf16_f32 v4, v4, v17
	v_mad_i64_i32 v[8:9], s[0:1], v8, s2, v[22:23]
	global_store_short v[8:9], v4, off
	s_nop 0
	v_max_f32_e32 v4, 0, v5
	v_mul_f32_e32 v4, v4, v4
	v_cvt_pk_bf16_f32 v10, v4, v17
	v_or_b32_e32 v4, 17, v31
	v_mad_i64_i32 v[4:5], s[0:1], v4, s2, v[22:23]
	v_max_f32_e32 v6, 0, v6
	global_store_short v[4:5], v10, off
	v_mul_f32_e32 v6, v6, v6
	v_or_b32_e32 v10, 18, v31
	v_cvt_pk_bf16_f32 v6, v6, v17
	v_mad_i64_i32 v[10:11], s[0:1], v10, s2, v[22:23]
	global_store_short v[10:11], v6, off
	s_nop 0
	v_max_f32_e32 v6, 0, v7
	v_mul_f32_e32 v6, v6, v6
	s_nop 0
	v_cvt_pk_bf16_f32 v12, v6, v17
	v_or_b32_e32 v6, 19, v31
	v_max_f32_e32 v0, 0, v0
	v_mad_i64_i32 v[6:7], s[0:1], v6, s2, v[22:23]
	v_mul_f32_e32 v0, v0, v0
	global_store_short v[6:7], v12, off
	v_cvt_pk_bf16_f32 v0, v0, v17
	global_store_short v[8:9], v0, off offset:32
	s_nop 0
	v_max_f32_e32 v0, 0, v1
	v_mul_f32_e32 v0, v0, v0
	v_cvt_pk_bf16_f32 v0, v0, v17
	global_store_short v[4:5], v0, off offset:32
	s_nop 0
	v_max_f32_e32 v0, 0, v2
	v_mul_f32_e32 v0, v0, v0
	v_cvt_pk_bf16_f32 v0, v0, v17
	v_readlane_b32 s0, v255, 8
	global_store_short v[10:11], v0, off offset:32
	s_nop 0
	v_add_u32_e32 v26, s0, v26
	s_movk_i32 s0, 0x7ff
	v_max_f32_e32 v0, 0, v3
	v_cmp_lt_i32_e32 vcc, s0, v26
	v_readlane_b32 s0, v254, 48
	v_mul_f32_e32 v0, v0, v0
	s_or_b64 s[14:15], vcc, s[14:15]
	v_add_u32_e32 v29, s0, v29
	v_cvt_pk_bf16_f32 v0, v0, v17
	global_store_short v[6:7], v0, off offset:32
	v_readlane_b32 s1, v255, 9
	s_andn2_b64 exec, exec, s[14:15]
	s_cbranch_execnz .LBB0_3787

; #define PG8_STAGE(bufoff, gbase, voff) do { _Pragma("unroll") for (int _i = 0; _i < 2; ++_i) \
;     __builtin_amdgcn_global_load_lds((const unsigned*)((const char*)(gbase) + (voff)[_i]), (LAS unsigned*)(lds + (bufoff) + ldsw + _i * 8192), 16, 0, 0); } while (0)
; #define PG8_LDA(dst, b, h) do { _Pragma("unroll") for (int m = 0; m < 4; ++m) _Pragma("unroll") for (int k = 0; k < 2; ++k) dst[m][k] = *(const LAS bf16x8*)(lds + PG8_SA(b, h) + aoff + m * 2048 + k * 1024); } while (0)
; #define PG8_LDB(dst, b, h) do { _Pragma("unroll") for (int n = 0; n < 2; ++n) _Pragma("unroll") for (int k = 0; k < 2; ++k) dst[n][k] = *(const LAS bf16x8*)(lds + PG8_SB(b, h) + boff + n * 2048 + k * 1024); } while (0)
; #define PG8_MMA(ai, bj, At, Bt) do { __builtin_amdgcn_s_setprio(1); _Pragma("unroll") for (int m = 0; m < 4; ++m) _Pragma("unroll") for (int n = 0; n < 2; ++n) _Pragma("unroll") for (int k = 0; k < 2; ++k) \
;     acc[ai][bj][m][n] = __builtin_amdgcn_mfma_f32_16x16x32_bf16(Bt[n][k], At[m][k], acc[ai][bj][m][n], 0, 0, 0); __builtin_amdgcn_s_setprio(0); } while (0)
; #define PG8_WAIT_V(n) asm volatile("s_waitcnt vmcnt(" #n ")" ::: "memory")
; #define PG8_WAIT_L(n) asm volatile("s_waitcnt lgkmcnt(" #n ")" ::: "memory")
; #define PG8_BAR __builtin_amdgcn_s_barrier()
; #define PG8_SCHED __builtin_amdgcn_sched_barrier(0)
; template <class Epi>
; __device__ __forceinline__ void gemm_phase(LAS unsigned char* lds, const Gemm g, const StaticOrder& S, const Epi& E) {
;     ...
;       PG8_LDB(B0, 0, 0); PG8_SCHED; PG8_LDA(At, 0, 0); PG8_STAGE(PG8_SA(1, 1), a1 + hstepA, voffA);
;       PG8_WAIT_L(8); PG8_BAR; PG8_WAIT_L(0); PG8_MMA(0, 0, At, B0); PG8_BAR; PG8_SCHED;
;       PG8_LDB(B1, 0, 1); PG8_STAGE(PG8_SB(0, 0), b2, voffB);
;       PG8_BAR; PG8_WAIT_L(0); PG8_MMA(0, 1, At, B1); PG8_BAR;
;       PG8_LDA(At, 0, 1); PG8_STAGE(PG8_SA(0, 0), a2, voffA);
;       PG8_BAR; PG8_WAIT_L(0); PG8_MMA(1, 0, At, B0); PG8_BAR; PG8_SCHED;
;       PG8_STAGE(PG8_SB(0, 1), b2 + hstepB, voffB);
;       PG8_WAIT_V(6); PG8_BAR; PG8_MMA(1, 1, At, B1); PG8_BAR;
.LBB0_3803:
	s_add_u32 s20, s14, 0xfffc0080
	s_addc_u32 s21, s15, -1
	s_add_i32 s46, 0, 0x10000
	v_add_u32_e32 v145, s46, v143
	ds_read_b128 v[146:149], v145
	ds_read_b128 v[150:153], v145 offset:1024
	ds_read_b128 v[154:157], v145 offset:2048
	ds_read_b128 v[158:161], v145 offset:3072
	s_cmp_eq_u32 s45, 12
	s_cselect_b32 s23, s5, s21
	s_cselect_b32 s22, s41, s20
	s_cselect_b32 s21, s3, s44
	s_cselect_b32 s20, s42, s43
	v_lshl_add_u64 v[194:195], s[14:15], 0, v[138:139]
	s_add_i32 m0, s30, 0xc000
	ds_read_b128 v[162:165], v144
	ds_read_b128 v[166:169], v144 offset:1024
	ds_read_b128 v[170:173], v144 offset:2048
	ds_read_b128 v[174:177], v144 offset:3072
	ds_read_b128 v[178:181], v144 offset:4096
	ds_read_b128 v[182:185], v144 offset:5120
	ds_read_b128 v[186:189], v144 offset:6144
	ds_read_b128 v[190:193], v144 offset:7168
	global_load_lds_dwordx4 v[194:195], off
	v_lshl_add_u64 v[194:195], s[14:15], 0, v[140:141]
	s_add_i32 m0, s30, 0xe000
	s_nop 0
	global_load_lds_dwordx4 v[194:195], off
	s_waitcnt lgkmcnt(8)
	s_barrier
	s_waitcnt lgkmcnt(0)
	s_setprio 1
	s_waitcnt lgkmcnt(0)
	v_mfma_f32_16x16x32_bf16 v[126:129], v[146:149], v[162:165], v[126:129]
	v_mfma_f32_16x16x32_bf16 v[122:125], v[154:157], v[162:165], v[122:125]
	v_mfma_f32_16x16x32_bf16 v[110:113], v[146:149], v[170:173], v[110:113]
	v_mfma_f32_16x16x32_bf16 v[106:109], v[154:157], v[170:173], v[106:109]
	v_mfma_f32_16x16x32_bf16 v[94:97], v[146:149], v[178:181], v[94:97]
	v_mfma_f32_16x16x32_bf16 v[90:93], v[154:157], v[178:181], v[90:93]
	v_mfma_f32_16x16x32_bf16 v[78:81], v[146:149], v[186:189], v[78:81]
	v_mfma_f32_16x16x32_bf16 v[74:77], v[154:157], v[186:189], v[74:77]
	v_mfma_f32_16x16x32_bf16 v[126:129], v[150:153], v[166:169], v[126:129]
	v_mfma_f32_16x16x32_bf16 v[122:125], v[158:161], v[166:169], v[122:125]
	v_mfma_f32_16x16x32_bf16 v[110:113], v[150:153], v[174:177], v[110:113]
	v_mfma_f32_16x16x32_bf16 v[106:109], v[158:161], v[174:177], v[106:109]
	v_mfma_f32_16x16x32_bf16 v[94:97], v[150:153], v[182:185], v[94:97]
	v_mfma_f32_16x16x32_bf16 v[90:93], v[158:161], v[182:185], v[90:93]
	v_mfma_f32_16x16x32_bf16 v[78:81], v[150:153], v[190:193], v[78:81]
	v_mfma_f32_16x16x32_bf16 v[74:77], v[158:161], v[190:193], v[74:77]
	s_setprio 0
	s_barrier
	s_add_i32 s48, 0, 0x14000
	s_add_i32 s46, s46, s29
	v_add_u32_e32 v145, s48, v143
	v_lshl_add_u64 v[210:211], s[20:21], 0, v[134:135]
	s_mov_b32 m0, s46
	ds_read_b128 v[194:197], v145
	ds_read_b128 v[198:201], v145 offset:1024
	ds_read_b128 v[202:205], v145 offset:2048
	ds_read_b128 v[206:209], v145 offset:3072
	global_load_lds_dwordx4 v[210:211], off
	v_lshl_add_u64 v[212:213], s[20:21], 0, v[130:131]
	s_add_i32 m0, s46, 0x2000
	s_nop 0
	global_load_lds_dwordx4 v[212:213], off
	s_barrier
	s_waitcnt lgkmcnt(0)
	s_setprio 1
	s_waitcnt lgkmcnt(0)
	v_mfma_f32_16x16x32_bf16 v[118:121], v[194:197], v[162:165], v[118:121]
	v_mfma_f32_16x16x32_bf16 v[114:117], v[202:205], v[162:165], v[114:117]
	v_mfma_f32_16x16x32_bf16 v[102:105], v[194:197], v[170:173], v[102:105]
	v_mfma_f32_16x16x32_bf16 v[98:101], v[202:205], v[170:173], v[98:101]
	v_mfma_f32_16x16x32_bf16 v[86:89], v[194:197], v[178:181], v[86:89]
	v_mfma_f32_16x16x32_bf16 v[82:85], v[202:205], v[178:181], v[82:85]
	v_mfma_f32_16x16x32_bf16 v[70:73], v[194:197], v[186:189], v[70:73]
	v_mfma_f32_16x16x32_bf16 v[66:69], v[202:205], v[186:189], v[66:69]
	v_mfma_f32_16x16x32_bf16 v[118:121], v[198:201], v[166:169], v[118:121]
	v_mfma_f32_16x16x32_bf16 v[114:117], v[206:209], v[166:169], v[114:117]
	v_mfma_f32_16x16x32_bf16 v[102:105], v[198:201], v[174:177], v[102:105]
	v_mfma_f32_16x16x32_bf16 v[98:101], v[206:209], v[174:177], v[98:101]
	v_mfma_f32_16x16x32_bf16 v[86:89], v[198:201], v[182:185], v[86:89]
	v_mfma_f32_16x16x32_bf16 v[82:85], v[206:209], v[182:185], v[82:85]
	v_mfma_f32_16x16x32_bf16 v[70:73], v[198:201], v[190:193], v[70:73]
	v_mfma_f32_16x16x32_bf16 v[66:69], v[206:209], v[190:193], v[66:69]
	s_setprio 0
	s_mov_b32 m0, s30
	v_lshl_add_u64 v[214:215], s[22:23], 0, v[136:137]
	s_barrier
	ds_read_b128 v[162:165], v144 offset:16384
	ds_read_b128 v[166:169], v144 offset:17408
	ds_read_b128 v[170:173], v144 offset:18432
	ds_read_b128 v[174:177], v144 offset:19456
	ds_read_b128 v[178:181], v144 offset:20480
	ds_read_b128 v[182:185], v144 offset:21504
	ds_read_b128 v[186:189], v144 offset:22528
	ds_read_b128 v[190:193], v144 offset:23552
	global_load_lds_dwordx4 v[214:215], off
	v_lshl_add_u64 v[216:217], s[22:23], 0, v[132:133]
	s_mov_b32 m0, s31
	s_nop 0
	global_load_lds_dwordx4 v[216:217], off
	s_barrier
	s_waitcnt lgkmcnt(0)
	s_setprio 1
	s_waitcnt lgkmcnt(0)
	v_mfma_f32_16x16x32_bf16 v[62:65], v[146:149], v[162:165], v[62:65]
	v_mfma_f32_16x16x32_bf16 v[58:61], v[154:157], v[162:165], v[58:61]
	v_mfma_f32_16x16x32_bf16 v[46:49], v[146:149], v[170:173], v[46:49]
	v_mfma_f32_16x16x32_bf16 v[42:45], v[154:157], v[170:173], v[42:45]
	v_mfma_f32_16x16x32_bf16 v[30:33], v[146:149], v[178:181], v[30:33]
	v_mfma_f32_16x16x32_bf16 v[26:29], v[154:157], v[178:181], v[26:29]
	v_mfma_f32_16x16x32_bf16 v[12:15], v[146:149], v[186:189], v[12:15]
	v_mfma_f32_16x16x32_bf16 v[8:11], v[154:157], v[186:189], v[8:11]
	v_mfma_f32_16x16x32_bf16 v[62:65], v[150:153], v[166:169], v[62:65]
	v_mfma_f32_16x16x32_bf16 v[58:61], v[158:161], v[166:169], v[58:61]
	v_mfma_f32_16x16x32_bf16 v[46:49], v[150:153], v[174:177], v[46:49]
	v_mfma_f32_16x16x32_bf16 v[42:45], v[158:161], v[174:177], v[42:45]
	v_mfma_f32_16x16x32_bf16 v[30:33], v[150:153], v[182:185], v[30:33]
	v_mfma_f32_16x16x32_bf16 v[26:29], v[158:161], v[182:185], v[26:29]
	v_mfma_f32_16x16x32_bf16 v[12:15], v[150:153], v[190:193], v[12:15]
	v_mfma_f32_16x16x32_bf16 v[8:11], v[158:161], v[190:193], v[8:11]
	s_setprio 0
	s_barrier
; #define PG8_STAGE(bufoff, gbase, voff) do { _Pragma("unroll") for (int _i = 0; _i < 2; ++_i) \
;     __builtin_amdgcn_global_load_lds((const unsigned*)((const char*)(gbase) + (voff)[_i]), (LAS unsigned*)(lds + (bufoff) + ldsw + _i * 8192), 16, 0, 0); } while (0)
; #define PG8_LDA(dst, b, h) do { _Pragma("unroll") for (int m = 0; m < 4; ++m) _Pragma("unroll") for (int k = 0; k < 2; ++k) dst[m][k] = *(const LAS bf16x8*)(lds + PG8_SA(b, h) + aoff + m * 2048 + k * 1024); } while (0)
; #define PG8_LDB(dst, b, h) do { _Pragma("unroll") for (int n = 0; n < 2; ++n) _Pragma("unroll") for (int k = 0; k < 2; ++k) dst[n][k] = *(const LAS bf16x8*)(lds + PG8_SB(b, h) + boff + n * 2048 + k * 1024); } while (0)
; #define PG8_MMA(ai, bj, At, Bt) do { __builtin_amdgcn_s_setprio(1); _Pragma("unroll") for (int m = 0; m < 4; ++m) _Pragma("unroll") for (int n = 0; n < 2; ++n) _Pragma("unroll") for (int k = 0; k < 2; ++k) \
;     acc[ai][bj][m][n] = __builtin_amdgcn_mfma_f32_16x16x32_bf16(Bt[n][k], At[m][k], acc[ai][bj][m][n], 0, 0, 0); __builtin_amdgcn_s_setprio(0); } while (0)
; #define PG8_WAIT_V(n) asm volatile("s_waitcnt vmcnt(" #n ")" ::: "memory")
; #define PG8_WAIT_L(n) asm volatile("s_waitcnt lgkmcnt(" #n ")" ::: "memory")
; #define PG8_BAR __builtin_amdgcn_s_barrier()
; #define PG8_SCHED __builtin_amdgcn_sched_barrier(0)
; template <class Epi>
; __device__ __forceinline__ void gemm_phase(LAS unsigned char* lds, const Gemm g, const StaticOrder& S, const Epi& E) {
;     ...
;       PG8_WAIT_V(6); PG8_BAR; PG8_MMA(1, 1, At, B1); PG8_BAR;
;       PG8_LDB(B0, 1, 0); PG8_SCHED; PG8_LDA(At, 1, 0); PG8_STAGE(PG8_SA(0, 1), a2 + hstepA, voffA);
;       PG8_WAIT_L(8); PG8_BAR; PG8_WAIT_L(0); PG8_MMA(0, 0, At, B0); PG8_BAR; PG8_SCHED;
;       PG8_LDB(B1, 1, 1); PG8_STAGE(PG8_SB(1, 0), b3, voffB);
;       PG8_BAR; PG8_WAIT_L(0); PG8_MMA(0, 1, At, B1); PG8_BAR;
;       PG8_LDA(At, 1, 1); PG8_STAGE(PG8_SA(1, 0), a3, voffA);
;       PG8_BAR; PG8_WAIT_L(0); PG8_MMA(1, 0, At, B0); PG8_BAR; PG8_SCHED;
	s_add_u32 s46, s20, 0x40000
	s_addc_u32 s47, s21, 0
	s_add_i32 s48, s48, s29
	v_lshl_add_u64 v[146:147], s[46:47], 0, v[134:135]
	s_mov_b32 m0, s48
	s_nop 0
	global_load_lds_dwordx4 v[146:147], off
	v_lshl_add_u64 v[146:147], s[46:47], 0, v[130:131]
	s_add_i32 m0, s48, 0x2000
	s_nop 0
	global_load_lds_dwordx4 v[146:147], off
	s_waitcnt vmcnt(6)
	s_barrier
	s_setprio 1
	v_mfma_f32_16x16x32_bf16 v[54:57], v[194:197], v[162:165], v[54:57]
	v_mfma_f32_16x16x32_bf16 v[50:53], v[202:205], v[162:165], v[50:53]
	v_mfma_f32_16x16x32_bf16 v[38:41], v[194:197], v[170:173], v[38:41]
	v_mfma_f32_16x16x32_bf16 v[34:37], v[202:205], v[170:173], v[34:37]
	v_mfma_f32_16x16x32_bf16 v[22:25], v[194:197], v[178:181], v[22:25]
	v_mfma_f32_16x16x32_bf16 v[18:21], v[202:205], v[178:181], v[18:21]
	v_mfma_f32_16x16x32_bf16 v[4:7], v[194:197], v[186:189], v[4:7]
	v_mfma_f32_16x16x32_bf16 v[0:3], v[202:205], v[186:189], v[0:3]
	v_mfma_f32_16x16x32_bf16 v[54:57], v[198:201], v[166:169], v[54:57]
	v_mfma_f32_16x16x32_bf16 v[50:53], v[206:209], v[166:169], v[50:53]
	v_mfma_f32_16x16x32_bf16 v[38:41], v[198:201], v[174:177], v[38:41]
	v_mfma_f32_16x16x32_bf16 v[34:37], v[206:209], v[174:177], v[34:37]
	v_mfma_f32_16x16x32_bf16 v[22:25], v[198:201], v[182:185], v[22:25]
	v_mfma_f32_16x16x32_bf16 v[18:21], v[206:209], v[182:185], v[18:21]
	v_mfma_f32_16x16x32_bf16 v[4:7], v[198:201], v[190:193], v[4:7]
	v_mfma_f32_16x16x32_bf16 v[0:3], v[206:209], v[190:193], v[0:3]
	s_setprio 0
	s_add_i32 s46, 0, 0x18000
	v_add_u32_e32 v145, s46, v143
	s_barrier
	ds_read_b128 v[146:149], v145
	ds_read_b128 v[150:153], v145 offset:1024
	ds_read_b128 v[154:157], v145 offset:2048
	ds_read_b128 v[158:161], v145 offset:3072
	s_add_u32 s22, s22, 0x40000
	s_addc_u32 s23, s23, 0
	s_mov_b32 m0, s34
	v_lshl_add_u64 v[194:195], s[22:23], 0, v[136:137]
	ds_read_b128 v[162:165], v144 offset:32768
	ds_read_b128 v[166:169], v144 offset:33792
	ds_read_b128 v[170:173], v144 offset:34816
	ds_read_b128 v[174:177], v144 offset:35840
	ds_read_b128 v[178:181], v144 offset:36864
	ds_read_b128 v[182:185], v144 offset:37888
	ds_read_b128 v[186:189], v144 offset:38912
	ds_read_b128 v[190:193], v144 offset:39936
	global_load_lds_dwordx4 v[194:195], off
	v_lshl_add_u64 v[194:195], s[22:23], 0, v[132:133]
	s_mov_b32 m0, s35
	s_nop 0
	global_load_lds_dwordx4 v[194:195], off
	s_waitcnt lgkmcnt(8)
	s_barrier
	s_waitcnt lgkmcnt(0)
	s_setprio 1
	s_waitcnt lgkmcnt(0)
	v_mfma_f32_16x16x32_bf16 v[126:129], v[146:149], v[162:165], v[126:129]
	v_mfma_f32_16x16x32_bf16 v[122:125], v[154:157], v[162:165], v[122:125]
	v_mfma_f32_16x16x32_bf16 v[110:113], v[146:149], v[170:173], v[110:113]
	v_mfma_f32_16x16x32_bf16 v[106:109], v[154:157], v[170:173], v[106:109]
	v_mfma_f32_16x16x32_bf16 v[94:97], v[146:149], v[178:181], v[94:97]
	v_mfma_f32_16x16x32_bf16 v[90:93], v[154:157], v[178:181], v[90:93]
	v_mfma_f32_16x16x32_bf16 v[78:81], v[146:149], v[186:189], v[78:81]
	v_mfma_f32_16x16x32_bf16 v[74:77], v[154:157], v[186:189], v[74:77]
	v_mfma_f32_16x16x32_bf16 v[126:129], v[150:153], v[166:169], v[126:129]
	v_mfma_f32_16x16x32_bf16 v[122:125], v[158:161], v[166:169], v[122:125]
	v_mfma_f32_16x16x32_bf16 v[110:113], v[150:153], v[174:177], v[110:113]
	v_mfma_f32_16x16x32_bf16 v[106:109], v[158:161], v[174:177], v[106:109]
	v_mfma_f32_16x16x32_bf16 v[94:97], v[150:153], v[182:185], v[94:97]
	v_mfma_f32_16x16x32_bf16 v[90:93], v[158:161], v[182:185], v[90:93]
	v_mfma_f32_16x16x32_bf16 v[78:81], v[150:153], v[190:193], v[78:81]
	v_mfma_f32_16x16x32_bf16 v[74:77], v[158:161], v[190:193], v[74:77]
	s_setprio 0
	s_barrier
	s_add_i32 s22, 0, 0x1c000
	s_add_i32 s23, s46, s29
	v_add_u32_e32 v145, s22, v143
	v_lshl_add_u64 v[210:211], v[210:211], 0, s[16:17]
	s_mov_b32 m0, s23
	ds_read_b128 v[194:197], v145
	ds_read_b128 v[198:201], v145 offset:1024
	ds_read_b128 v[202:205], v145 offset:2048
	ds_read_b128 v[206:209], v145 offset:3072
	global_load_lds_dwordx4 v[210:211], off
	v_lshl_add_u64 v[210:211], v[212:213], 0, s[16:17]
	s_add_i32 m0, s23, 0x2000
	s_nop 0
	global_load_lds_dwordx4 v[210:211], off
	s_barrier
	s_waitcnt lgkmcnt(0)
	s_setprio 1
	s_waitcnt lgkmcnt(0)
	v_mfma_f32_16x16x32_bf16 v[118:121], v[194:197], v[162:165], v[118:121]
	v_mfma_f32_16x16x32_bf16 v[114:117], v[202:205], v[162:165], v[114:117]
	v_mfma_f32_16x16x32_bf16 v[102:105], v[194:197], v[170:173], v[102:105]
	v_mfma_f32_16x16x32_bf16 v[98:101], v[202:205], v[170:173], v[98:101]
	v_mfma_f32_16x16x32_bf16 v[86:89], v[194:197], v[178:181], v[86:89]
	v_mfma_f32_16x16x32_bf16 v[82:85], v[202:205], v[178:181], v[82:85]
	v_mfma_f32_16x16x32_bf16 v[70:73], v[194:197], v[186:189], v[70:73]
	v_mfma_f32_16x16x32_bf16 v[66:69], v[202:205], v[186:189], v[66:69]
	v_mfma_f32_16x16x32_bf16 v[118:121], v[198:201], v[166:169], v[118:121]
	v_mfma_f32_16x16x32_bf16 v[114:117], v[206:209], v[166:169], v[114:117]
	v_mfma_f32_16x16x32_bf16 v[102:105], v[198:201], v[174:177], v[102:105]
	v_mfma_f32_16x16x32_bf16 v[98:101], v[206:209], v[174:177], v[98:101]
	v_mfma_f32_16x16x32_bf16 v[86:89], v[198:201], v[182:185], v[86:89]
	v_mfma_f32_16x16x32_bf16 v[82:85], v[206:209], v[182:185], v[82:85]
	v_mfma_f32_16x16x32_bf16 v[70:73], v[198:201], v[190:193], v[70:73]
	v_mfma_f32_16x16x32_bf16 v[66:69], v[206:209], v[190:193], v[66:69]
	s_setprio 0
	s_mov_b32 m0, s36
	v_lshl_add_u64 v[210:211], v[214:215], 0, s[16:17]
	s_barrier
	ds_read_b128 v[162:165], v144 offset:49152
	ds_read_b128 v[166:169], v144 offset:50176
	ds_read_b128 v[170:173], v144 offset:51200
	ds_read_b128 v[174:177], v144 offset:52224
	ds_read_b128 v[178:181], v144 offset:53248
	ds_read_b128 v[182:185], v144 offset:54272
	ds_read_b128 v[186:189], v144 offset:55296
	ds_read_b128 v[190:193], v144 offset:56320
	global_load_lds_dwordx4 v[210:211], off
	v_lshl_add_u64 v[210:211], v[216:217], 0, s[16:17]
	s_mov_b32 m0, s37
	s_nop 0
	global_load_lds_dwordx4 v[210:211], off
	s_barrier
; #define PG8_STAGE(bufoff, gbase, voff) do { _Pragma("unroll") for (int _i = 0; _i < 2; ++_i) \
;     __builtin_amdgcn_global_load_lds((const unsigned*)((const char*)(gbase) + (voff)[_i]), (LAS unsigned*)(lds + (bufoff) + ldsw + _i * 8192), 16, 0, 0); } while (0)
; #define PG8_MMA(ai, bj, At, Bt) do { __builtin_amdgcn_s_setprio(1); _Pragma("unroll") for (int m = 0; m < 4; ++m) _Pragma("unroll") for (int n = 0; n < 2; ++n) _Pragma("unroll") for (int k = 0; k < 2; ++k) \
;     acc[ai][bj][m][n] = __builtin_amdgcn_mfma_f32_16x16x32_bf16(Bt[n][k], At[m][k], acc[ai][bj][m][n], 0, 0, 0); __builtin_amdgcn_s_setprio(0); } while (0)
; #define PG8_WAIT_V(n) asm volatile("s_waitcnt vmcnt(" #n ")" ::: "memory")
; #define PG8_WAIT_L(n) asm volatile("s_waitcnt lgkmcnt(" #n ")" ::: "memory")
; #define PG8_BAR __builtin_amdgcn_s_barrier()
; #define PG8_SCHED __builtin_amdgcn_sched_barrier(0)
; template <class Epi>
; __device__ __forceinline__ void gemm_phase(LAS unsigned char* lds, const Gemm g, const StaticOrder& S, const Epi& E) {
;     ...
;       PG8_BAR; PG8_WAIT_L(0); PG8_MMA(1, 0, At, B0); PG8_BAR; PG8_SCHED;
;       PG8_STAGE(PG8_SB(1, 1), b3 + hstepB, voffB);
;       PG8_WAIT_V(6); PG8_BAR; PG8_MMA(1, 1, At, B1); PG8_BAR;
;     }
;   __device__ __forceinline__ void operator()(const f32x4 (&acc)[2][2][4][2], const Unit& u, int wr, int wc, int fr, int fq) const {
;     ...
;     for (int ai = 0; ai < 2; ++ai)
; #pragma unroll
;       for (int m = 0; m < 4; ++m) {
;         const int r = u.pm * 256 + ai * 128 + wr * 64 + m * 16 + fr;
; #pragma unroll
;         for (int bj = 0; bj < 2; ++bj) {
;           float v[8];
; #pragma unroll
;           for (int e = 0; e < 4; ++e) {
;             const float a = fmaxf(acc[ai][bj][m][0][e], 0.f), b = fmaxf(acc[ai][bj][m][1][e], 0.f);
;             v[e] = a * a; v[4 + e] = b * b;
;           }
;           u32x4 w;
; #pragma unroll
;           for (int e = 0; e < 4; ++e) w[e] = cvt_pk_bf16(v[2 * e], v[2 * e + 1]);
;           *(u32x4*)(H + (size_t)r * LDH + u.pn * 256 + bj * 128 + wc * 32 + 8 * fq) = w;
;         }
	s_waitcnt lgkmcnt(0)
	s_setprio 1
	s_waitcnt lgkmcnt(0)
	v_mfma_f32_16x16x32_bf16 v[62:65], v[146:149], v[162:165], v[62:65]
	v_mfma_f32_16x16x32_bf16 v[58:61], v[154:157], v[162:165], v[58:61]
	v_mfma_f32_16x16x32_bf16 v[46:49], v[146:149], v[170:173], v[46:49]
	v_mfma_f32_16x16x32_bf16 v[42:45], v[154:157], v[170:173], v[42:45]
	v_mfma_f32_16x16x32_bf16 v[30:33], v[146:149], v[178:181], v[30:33]
	v_mfma_f32_16x16x32_bf16 v[26:29], v[154:157], v[178:181], v[26:29]
	v_mfma_f32_16x16x32_bf16 v[12:15], v[146:149], v[186:189], v[12:15]
	v_mfma_f32_16x16x32_bf16 v[8:11], v[154:157], v[186:189], v[8:11]
	v_mfma_f32_16x16x32_bf16 v[62:65], v[150:153], v[166:169], v[62:65]
	v_mfma_f32_16x16x32_bf16 v[58:61], v[158:161], v[166:169], v[58:61]
	v_mfma_f32_16x16x32_bf16 v[46:49], v[150:153], v[174:177], v[46:49]
	v_mfma_f32_16x16x32_bf16 v[42:45], v[158:161], v[174:177], v[42:45]
	v_mfma_f32_16x16x32_bf16 v[30:33], v[150:153], v[182:185], v[30:33]
	v_mfma_f32_16x16x32_bf16 v[26:29], v[158:161], v[182:185], v[26:29]
	v_mfma_f32_16x16x32_bf16 v[12:15], v[150:153], v[190:193], v[12:15]
	v_mfma_f32_16x16x32_bf16 v[8:11], v[158:161], v[190:193], v[8:11]
	s_setprio 0
	s_barrier
	s_add_u32 s20, s20, 0x40080
	s_addc_u32 s21, s21, 0
	s_add_i32 s22, s22, s29
	v_lshl_add_u64 v[146:147], s[20:21], 0, v[134:135]
	s_mov_b32 m0, s22
	s_nop 0
	global_load_lds_dwordx4 v[146:147], off
	v_lshl_add_u64 v[146:147], s[20:21], 0, v[130:131]
	s_add_i32 m0, s22, 0x2000
	s_nop 0
	global_load_lds_dwordx4 v[146:147], off
	s_waitcnt vmcnt(6)
	s_barrier
	s_setprio 1
	v_mfma_f32_16x16x32_bf16 v[54:57], v[194:197], v[162:165], v[54:57]
	v_mfma_f32_16x16x32_bf16 v[50:53], v[202:205], v[162:165], v[50:53]
	v_mfma_f32_16x16x32_bf16 v[38:41], v[194:197], v[170:173], v[38:41]
	v_mfma_f32_16x16x32_bf16 v[34:37], v[202:205], v[170:173], v[34:37]
	v_mfma_f32_16x16x32_bf16 v[22:25], v[194:197], v[178:181], v[22:25]
	v_mfma_f32_16x16x32_bf16 v[18:21], v[202:205], v[178:181], v[18:21]
	v_mfma_f32_16x16x32_bf16 v[4:7], v[194:197], v[186:189], v[4:7]
	v_mfma_f32_16x16x32_bf16 v[0:3], v[202:205], v[186:189], v[0:3]
	v_mfma_f32_16x16x32_bf16 v[54:57], v[198:201], v[166:169], v[54:57]
	v_mfma_f32_16x16x32_bf16 v[50:53], v[206:209], v[166:169], v[50:53]
	v_mfma_f32_16x16x32_bf16 v[38:41], v[198:201], v[174:177], v[38:41]
	v_mfma_f32_16x16x32_bf16 v[34:37], v[206:209], v[174:177], v[34:37]
	v_mfma_f32_16x16x32_bf16 v[22:25], v[198:201], v[182:185], v[22:25]
	v_mfma_f32_16x16x32_bf16 v[18:21], v[206:209], v[182:185], v[18:21]
	v_mfma_f32_16x16x32_bf16 v[4:7], v[198:201], v[190:193], v[4:7]
	v_mfma_f32_16x16x32_bf16 v[0:3], v[206:209], v[190:193], v[0:3]
	s_setprio 0
	s_add_i32 s45, s45, 2
	s_add_u32 s14, s14, 0x100
	s_addc_u32 s15, s15, 0
	s_add_u32 s43, s43, 0x100
	s_addc_u32 s44, s44, 0
	s_cmp_gt_u32 s45, 13
	s_barrier
	s_cbranch_scc0 .LBB0_3803
	v_max_f32_e32 v124, 0, v124
	v_max_f32_e32 v126, 0, v126
	v_max_f32_e32 v122, 0, v122
	v_max_f32_e32 v123, 0, v123
	v_mul_f32_e32 v146, v124, v124
	s_lshl_b32 s14, s39, 8
	v_mul_f32_e32 v126, v126, v126
	v_mul_f32_e32 v122, v122, v122
	v_max_f32_e32 v127, 0, v127
	v_mul_f32_e32 v123, v123, v123
	v_max_f32_e32 v128, 0, v128
	v_max_f32_e32 v124, 0, v129
	v_max_f32_e32 v125, 0, v125
	v_lshl_add_u32 v145, s40, 8, v142
	s_ashr_i32 s15, s14, 31
	v_mul_f32_e32 v127, v127, v127
	v_mul_f32_e32 v128, v128, v128
	v_mul_f32_e32 v129, v124, v124
	v_mul_f32_e32 v147, v125, v125
	v_cvt_pk_bf16_f32 v124, v126, v127
	v_cvt_pk_bf16_f32 v125, v128, v129
	v_cvt_pk_bf16_f32 v126, v122, v123
	v_mov_b64_e32 v[122:123], s[0:1]
	s_movk_i32 s3, 0x2080
	v_mad_i64_i32 v[128:129], s[20:21], v145, s3, v[122:123]
	s_lshl_b64 s[14:15], s[14:15], 1
	v_readlane_b32 s22, v255, 20
	v_lshl_add_u64 v[128:129], v[128:129], 0, s[14:15]
	v_readlane_b32 s23, v255, 21
	s_nop 0
	s_nop 0
	v_lshl_add_u64 v[128:129], v[128:129], 0, s[22:23]
	v_lshl_add_u64 v[128:129], v[128:129], 0, v[16:17]
	v_max_f32_e32 v114, 0, v114
	v_max_f32_e32 v115, 0, v115
	v_cvt_pk_bf16_f32 v127, v146, v147
	global_store_dwordx4 v[128:129], v[124:127], off
	v_max_f32_e32 v116, 0, v116
	s_nop 0
	v_mul_f32_e32 v124, v114, v114
	v_max_f32_e32 v114, v119, v119
	v_mul_f32_e32 v119, v115, v115
	v_max_f32_e32 v114, 0, v114
	v_max_f32_e32 v115, 0, v120
	v_mul_f32_e32 v120, v116, v116
	v_max_f32_e32 v118, 0, v118
	v_mul_f32_e32 v114, v114, v114
	v_mul_f32_e32 v115, v115, v115
	v_max_f32_e32 v116, 0, v121
	v_max_f32_e32 v117, 0, v117
	v_mul_f32_e32 v118, v118, v118
	v_mul_f32_e32 v116, v116, v116
	v_mul_f32_e32 v117, v117, v117
	v_cvt_pk_bf16_f32 v114, v118, v114
	v_cvt_pk_bf16_f32 v115, v115, v116
	v_max_f32_e32 v106, 0, v106
	v_max_f32_e32 v107, 0, v107
	v_max_f32_e32 v108, 0, v108
	v_cvt_pk_bf16_f32 v116, v124, v119
	v_cvt_pk_bf16_f32 v117, v120, v117
	global_store_dwordx4 v[128:129], v[114:117], off offset:256
	s_nop 0
	v_max_f32_e32 v110, 0, v110
	v_mul_f32_e32 v115, v106, v106
	v_max_f32_e32 v106, v111, v111
	v_mul_f32_e32 v111, v107, v107
	v_max_f32_e32 v107, v112, v112
	v_mul_f32_e32 v112, v108, v108
	v_max_f32_e32 v106, 0, v106
	v_max_f32_e32 v107, 0, v107
	v_max_f32_e32 v108, 0, v113
	v_or_b32_e32 v114, 16, v145
	v_mul_f32_e32 v110, v110, v110
	v_mul_f32_e32 v106, v106, v106
	v_mul_f32_e32 v107, v107, v107
	v_mul_f32_e32 v108, v108, v108
	v_cvt_pk_bf16_f32 v106, v110, v106
	v_cvt_pk_bf16_f32 v107, v107, v108
	v_cvt_pk_bf16_f32 v108, v115, v111
	v_mad_i64_i32 v[110:111], s[20:21], v114, s3, v[122:123]
	s_nop 0
	v_lshl_add_u64 v[110:111], v[110:111], 0, s[14:15]
	v_max_f32_e32 v109, 0, v109
	v_lshl_add_u64 v[110:111], v[110:111], 0, s[22:23]
	s_nop 0
	v_mul_f32_e32 v109, v109, v109
	v_lshl_add_u64 v[110:111], v[110:111], 0, v[16:17]
;   __device__ __forceinline__ void operator()(const f32x4 (&acc)[2][2][4][2], const Unit& u, int wr, int wc, int fr, int fq) const {
;     ...
;     for (int ai = 0; ai < 2; ++ai)
; #pragma unroll
;       for (int m = 0; m < 4; ++m) {
;         const int r = u.pm * 256 + ai * 128 + wr * 64 + m * 16 + fr;
; #pragma unroll
;         for (int bj = 0; bj < 2; ++bj) {
;           float v[8];
; #pragma unroll
;           for (int e = 0; e < 4; ++e) {
;             const float a = fmaxf(acc[ai][bj][m][0][e], 0.f), b = fmaxf(acc[ai][bj][m][1][e], 0.f);
;             v[e] = a * a; v[4 + e] = b * b;
;           }
;           u32x4 w;
; #pragma unroll
;           for (int e = 0; e < 4; ++e) w[e] = cvt_pk_bf16(v[2 * e], v[2 * e + 1]);
;           *(u32x4*)(H + (size_t)r * LDH + u.pn * 256 + bj * 128 + wc * 32 + 8 * fq) = w;
;         }
	v_max_f32_e32 v98, 0, v98
	v_max_f32_e32 v99, 0, v99
	v_cvt_pk_bf16_f32 v109, v112, v109
	global_store_dwordx4 v[110:111], v[106:109], off
	v_max_f32_e32 v100, 0, v100
	s_nop 0
	v_mul_f32_e32 v106, v98, v98
	v_max_f32_e32 v98, v103, v103
	v_mul_f32_e32 v103, v99, v99
	v_max_f32_e32 v98, 0, v98
	v_max_f32_e32 v99, 0, v104
	v_mul_f32_e32 v104, v100, v100
	v_max_f32_e32 v102, 0, v102
	v_mul_f32_e32 v98, v98, v98
	v_mul_f32_e32 v99, v99, v99
	v_max_f32_e32 v100, 0, v105
	v_max_f32_e32 v101, 0, v101
	v_mul_f32_e32 v102, v102, v102
	v_mul_f32_e32 v100, v100, v100
	v_mul_f32_e32 v101, v101, v101
	v_cvt_pk_bf16_f32 v98, v102, v98
	v_cvt_pk_bf16_f32 v99, v99, v100
	v_max_f32_e32 v90, 0, v90
	v_max_f32_e32 v91, 0, v91
	v_max_f32_e32 v92, 0, v92
	v_cvt_pk_bf16_f32 v100, v106, v103
	v_cvt_pk_bf16_f32 v101, v104, v101
	global_store_dwordx4 v[110:111], v[98:101], off offset:256
	s_nop 0
	v_max_f32_e32 v94, 0, v94
	v_mul_f32_e32 v99, v90, v90
	v_max_f32_e32 v90, v95, v95
	v_mul_f32_e32 v95, v91, v91
	v_max_f32_e32 v91, v96, v96
	v_mul_f32_e32 v96, v92, v92
	v_max_f32_e32 v90, 0, v90
	v_max_f32_e32 v91, 0, v91
	v_max_f32_e32 v92, 0, v97
	v_or_b32_e32 v98, 32, v145
	v_mul_f32_e32 v94, v94, v94
	v_mul_f32_e32 v90, v90, v90
	v_mul_f32_e32 v91, v91, v91
	v_mul_f32_e32 v92, v92, v92
	v_cvt_pk_bf16_f32 v90, v94, v90
	v_cvt_pk_bf16_f32 v91, v91, v92
	v_cvt_pk_bf16_f32 v92, v99, v95
	v_mad_i64_i32 v[94:95], s[20:21], v98, s3, v[122:123]
	s_nop 0
	v_lshl_add_u64 v[94:95], v[94:95], 0, s[14:15]
	v_max_f32_e32 v93, 0, v93
	v_lshl_add_u64 v[94:95], v[94:95], 0, s[22:23]
	s_nop 0
	v_mul_f32_e32 v93, v93, v93
	v_lshl_add_u64 v[94:95], v[94:95], 0, v[16:17]
	v_max_f32_e32 v82, 0, v82
	v_max_f32_e32 v83, 0, v83
	v_cvt_pk_bf16_f32 v93, v96, v93
	global_store_dwordx4 v[94:95], v[90:93], off
	v_max_f32_e32 v84, 0, v84
	s_nop 0
	v_mul_f32_e32 v90, v82, v82
	v_max_f32_e32 v82, v87, v87
	v_mul_f32_e32 v87, v83, v83
	v_max_f32_e32 v82, 0, v82
	v_max_f32_e32 v83, 0, v88
	v_mul_f32_e32 v88, v84, v84
	v_max_f32_e32 v86, 0, v86
	v_mul_f32_e32 v82, v82, v82
	v_mul_f32_e32 v83, v83, v83
	v_max_f32_e32 v84, 0, v89
	v_max_f32_e32 v85, 0, v85
	v_mul_f32_e32 v86, v86, v86
	v_mul_f32_e32 v84, v84, v84
	v_mul_f32_e32 v85, v85, v85
	v_cvt_pk_bf16_f32 v82, v86, v82
	v_cvt_pk_bf16_f32 v83, v83, v84
	v_max_f32_e32 v74, 0, v74
	v_max_f32_e32 v75, 0, v75
	v_max_f32_e32 v76, 0, v76
	v_cvt_pk_bf16_f32 v84, v90, v87
	v_cvt_pk_bf16_f32 v85, v88, v85
	global_store_dwordx4 v[94:95], v[82:85], off offset:256
	s_nop 0
	v_max_f32_e32 v78, 0, v78
	v_mul_f32_e32 v83, v74, v74
	v_max_f32_e32 v74, v79, v79
	v_mul_f32_e32 v79, v75, v75
	v_max_f32_e32 v75, v80, v80
	v_mul_f32_e32 v80, v76, v76
	v_max_f32_e32 v74, 0, v74
	v_max_f32_e32 v75, 0, v75
	v_max_f32_e32 v76, 0, v81
	v_or_b32_e32 v82, 48, v145
	v_mul_f32_e32 v78, v78, v78
	v_mul_f32_e32 v74, v74, v74
	v_mul_f32_e32 v75, v75, v75
	v_mul_f32_e32 v76, v76, v76
	v_cvt_pk_bf16_f32 v74, v78, v74
	v_cvt_pk_bf16_f32 v75, v75, v76
	v_cvt_pk_bf16_f32 v76, v83, v79
	v_mad_i64_i32 v[78:79], s[20:21], v82, s3, v[122:123]
	s_nop 0
	v_lshl_add_u64 v[78:79], v[78:79], 0, s[14:15]
	v_max_f32_e32 v77, 0, v77
	v_lshl_add_u64 v[78:79], v[78:79], 0, s[22:23]
	s_nop 0
	v_mul_f32_e32 v77, v77, v77
	v_lshl_add_u64 v[78:79], v[78:79], 0, v[16:17]
	v_max_f32_e32 v66, 0, v66
	v_max_f32_e32 v67, 0, v67
	v_cvt_pk_bf16_f32 v77, v80, v77
	global_store_dwordx4 v[78:79], v[74:77], off
	v_max_f32_e32 v68, 0, v68
	s_nop 0
	v_mul_f32_e32 v74, v66, v66
	v_max_f32_e32 v66, v71, v71
	v_mul_f32_e32 v71, v67, v67
	v_max_f32_e32 v66, 0, v66
	v_max_f32_e32 v67, 0, v72
	v_mul_f32_e32 v72, v68, v68
	v_max_f32_e32 v70, 0, v70
	v_mul_f32_e32 v66, v66, v66
	v_mul_f32_e32 v67, v67, v67
	v_max_f32_e32 v68, 0, v73
	v_max_f32_e32 v69, 0, v69
	v_mul_f32_e32 v70, v70, v70
	v_mul_f32_e32 v68, v68, v68
	v_mul_f32_e32 v69, v69, v69
	v_cvt_pk_bf16_f32 v66, v70, v66
	v_cvt_pk_bf16_f32 v67, v67, v68
	v_max_f32_e32 v58, 0, v58
	v_max_f32_e32 v59, 0, v59
	v_max_f32_e32 v60, 0, v60
	v_cvt_pk_bf16_f32 v68, v74, v71
	v_cvt_pk_bf16_f32 v69, v72, v69
	global_store_dwordx4 v[78:79], v[66:69], off offset:256
	s_nop 0
	v_max_f32_e32 v62, 0, v62
	v_mul_f32_e32 v67, v58, v58
	v_max_f32_e32 v58, v63, v63
	v_mul_f32_e32 v63, v59, v59
	v_max_f32_e32 v59, v64, v64
	v_mul_f32_e32 v64, v60, v60
	v_max_f32_e32 v58, 0, v58
	v_max_f32_e32 v59, 0, v59
	v_max_f32_e32 v60, 0, v65
	v_add_u32_e32 v66, 0x80, v145
	v_mul_f32_e32 v62, v62, v62
	v_mul_f32_e32 v58, v58, v58
	v_mul_f32_e32 v59, v59, v59
	v_mul_f32_e32 v60, v60, v60
	v_cvt_pk_bf16_f32 v58, v62, v58
	v_cvt_pk_bf16_f32 v59, v59, v60
	v_cvt_pk_bf16_f32 v60, v67, v63
	v_mad_i64_i32 v[62:63], s[20:21], v66, s3, v[122:123]
	s_nop 0
	v_lshl_add_u64 v[62:63], v[62:63], 0, s[14:15]
	v_max_f32_e32 v61, 0, v61
	v_lshl_add_u64 v[62:63], v[62:63], 0, s[22:23]
	s_nop 0
	v_mul_f32_e32 v61, v61, v61
	v_lshl_add_u64 v[62:63], v[62:63], 0, v[16:17]
	v_max_f32_e32 v50, 0, v50
	v_max_f32_e32 v51, 0, v51
	v_cvt_pk_bf16_f32 v61, v64, v61
	global_store_dwordx4 v[62:63], v[58:61], off
	v_max_f32_e32 v52, 0, v52
	s_nop 0
	v_mul_f32_e32 v58, v50, v50
	v_max_f32_e32 v50, v55, v55
	v_mul_f32_e32 v55, v51, v51
	v_max_f32_e32 v50, 0, v50
	v_max_f32_e32 v51, 0, v56
	v_mul_f32_e32 v56, v52, v52
	v_max_f32_e32 v54, 0, v54
	v_mul_f32_e32 v50, v50, v50
	v_mul_f32_e32 v51, v51, v51
;   __device__ __forceinline__ void operator()(const f32x4 (&acc)[2][2][4][2], const Unit& u, int wr, int wc, int fr, int fq) const {
;     ...
;     for (int ai = 0; ai < 2; ++ai)
; #pragma unroll
;       for (int m = 0; m < 4; ++m) {
;         const int r = u.pm * 256 + ai * 128 + wr * 64 + m * 16 + fr;
; #pragma unroll
;         for (int bj = 0; bj < 2; ++bj) {
;           float v[8];
; #pragma unroll
;           for (int e = 0; e < 4; ++e) {
;             const float a = fmaxf(acc[ai][bj][m][0][e], 0.f), b = fmaxf(acc[ai][bj][m][1][e], 0.f);
;             v[e] = a * a; v[4 + e] = b * b;
;           }
;           u32x4 w;
; #pragma unroll
;           for (int e = 0; e < 4; ++e) w[e] = cvt_pk_bf16(v[2 * e], v[2 * e + 1]);
;           *(u32x4*)(H + (size_t)r * LDH + u.pn * 256 + bj * 128 + wc * 32 + 8 * fq) = w;
;         }
	v_max_f32_e32 v52, 0, v57
	v_max_f32_e32 v53, 0, v53
	v_mul_f32_e32 v54, v54, v54
	v_mul_f32_e32 v52, v52, v52
	v_mul_f32_e32 v53, v53, v53
	v_cvt_pk_bf16_f32 v50, v54, v50
	v_cvt_pk_bf16_f32 v51, v51, v52
	v_max_f32_e32 v42, 0, v42
	v_max_f32_e32 v43, 0, v43
	v_max_f32_e32 v44, 0, v44
	v_cvt_pk_bf16_f32 v52, v58, v55
	v_cvt_pk_bf16_f32 v53, v56, v53
	global_store_dwordx4 v[62:63], v[50:53], off offset:256
	s_nop 0
	v_max_f32_e32 v46, 0, v46
	v_mul_f32_e32 v51, v42, v42
	v_max_f32_e32 v42, v47, v47
	v_mul_f32_e32 v47, v43, v43
	v_max_f32_e32 v43, v48, v48
	v_mul_f32_e32 v48, v44, v44
	v_max_f32_e32 v42, 0, v42
	v_max_f32_e32 v43, 0, v43
	v_max_f32_e32 v44, 0, v49
	v_add_u32_e32 v50, 0x90, v145
	v_mul_f32_e32 v46, v46, v46
	v_mul_f32_e32 v42, v42, v42
	v_mul_f32_e32 v43, v43, v43
	v_mul_f32_e32 v44, v44, v44
	v_cvt_pk_bf16_f32 v42, v46, v42
	v_cvt_pk_bf16_f32 v43, v43, v44
	v_cvt_pk_bf16_f32 v44, v51, v47
	v_mad_i64_i32 v[46:47], s[20:21], v50, s3, v[122:123]
	s_nop 0
	v_lshl_add_u64 v[46:47], v[46:47], 0, s[14:15]
	v_max_f32_e32 v45, 0, v45
	v_lshl_add_u64 v[46:47], v[46:47], 0, s[22:23]
	s_nop 0
	v_mul_f32_e32 v45, v45, v45
	v_lshl_add_u64 v[46:47], v[46:47], 0, v[16:17]
	v_max_f32_e32 v34, 0, v34
	v_max_f32_e32 v35, 0, v35
	v_cvt_pk_bf16_f32 v45, v48, v45
	global_store_dwordx4 v[46:47], v[42:45], off
	v_max_f32_e32 v36, 0, v36
	s_nop 0
	v_mul_f32_e32 v42, v34, v34
	v_max_f32_e32 v34, v39, v39
	v_mul_f32_e32 v39, v35, v35
	v_max_f32_e32 v34, 0, v34
	v_max_f32_e32 v35, 0, v40
	v_mul_f32_e32 v40, v36, v36
	v_max_f32_e32 v38, 0, v38
	v_mul_f32_e32 v34, v34, v34
	v_mul_f32_e32 v35, v35, v35
	v_max_f32_e32 v36, 0, v41
	v_max_f32_e32 v37, 0, v37
	v_mul_f32_e32 v38, v38, v38
	v_mul_f32_e32 v36, v36, v36
	v_mul_f32_e32 v37, v37, v37
	v_cvt_pk_bf16_f32 v34, v38, v34
	v_cvt_pk_bf16_f32 v35, v35, v36
	v_max_f32_e32 v26, 0, v26
	v_max_f32_e32 v27, 0, v27
	v_max_f32_e32 v28, 0, v28
	v_cvt_pk_bf16_f32 v36, v42, v39
	v_cvt_pk_bf16_f32 v37, v40, v37
	global_store_dwordx4 v[46:47], v[34:37], off offset:256
	s_nop 0
	v_max_f32_e32 v30, 0, v30
	v_mul_f32_e32 v35, v26, v26
	v_max_f32_e32 v26, v31, v31
	v_mul_f32_e32 v31, v27, v27
	v_max_f32_e32 v27, v32, v32
	v_mul_f32_e32 v32, v28, v28
	v_max_f32_e32 v26, 0, v26
	v_max_f32_e32 v27, 0, v27
	v_max_f32_e32 v28, 0, v33
	v_add_u32_e32 v34, 0xa0, v145
	v_mul_f32_e32 v30, v30, v30
	v_mul_f32_e32 v26, v26, v26
	v_mul_f32_e32 v27, v27, v27
	v_mul_f32_e32 v28, v28, v28
	v_cvt_pk_bf16_f32 v26, v30, v26
	v_cvt_pk_bf16_f32 v27, v27, v28
	v_cvt_pk_bf16_f32 v28, v35, v31
	v_mad_i64_i32 v[30:31], s[20:21], v34, s3, v[122:123]
	s_nop 0
	v_lshl_add_u64 v[30:31], v[30:31], 0, s[14:15]
	v_max_f32_e32 v29, 0, v29
	v_lshl_add_u64 v[30:31], v[30:31], 0, s[22:23]
	s_nop 0
	v_mul_f32_e32 v29, v29, v29
	v_lshl_add_u64 v[30:31], v[30:31], 0, v[16:17]
	v_max_f32_e32 v18, 0, v18
	v_max_f32_e32 v19, 0, v19
	v_cvt_pk_bf16_f32 v29, v32, v29
	global_store_dwordx4 v[30:31], v[26:29], off
	v_max_f32_e32 v20, 0, v20
	s_nop 0
	v_mul_f32_e32 v26, v18, v18
	v_max_f32_e32 v18, v23, v23
	v_mul_f32_e32 v23, v19, v19
	v_max_f32_e32 v18, 0, v18
	v_max_f32_e32 v19, 0, v24
	v_mul_f32_e32 v24, v20, v20
	v_max_f32_e32 v22, 0, v22
	v_mul_f32_e32 v18, v18, v18
	v_mul_f32_e32 v19, v19, v19
	v_max_f32_e32 v20, 0, v25
	v_max_f32_e32 v21, 0, v21
	v_mul_f32_e32 v22, v22, v22
	v_mul_f32_e32 v20, v20, v20
	v_mul_f32_e32 v21, v21, v21
	v_cvt_pk_bf16_f32 v18, v22, v18
	v_cvt_pk_bf16_f32 v19, v19, v20
	v_max_f32_e32 v8, 0, v8
	v_max_f32_e32 v9, 0, v9
	v_max_f32_e32 v10, 0, v10
	v_cvt_pk_bf16_f32 v20, v26, v23
	v_cvt_pk_bf16_f32 v21, v24, v21
	global_store_dwordx4 v[30:31], v[18:21], off offset:256
	s_nop 0
	v_max_f32_e32 v12, 0, v12
	v_mul_f32_e32 v19, v8, v8
	v_max_f32_e32 v8, v13, v13
	v_mul_f32_e32 v13, v9, v9
	v_max_f32_e32 v9, v14, v14
	v_mul_f32_e32 v14, v10, v10
	v_max_f32_e32 v8, 0, v8
	v_max_f32_e32 v9, 0, v9
	v_max_f32_e32 v10, 0, v15
	v_add_u32_e32 v18, 0xb0, v145
	v_mul_f32_e32 v12, v12, v12
	v_mul_f32_e32 v8, v8, v8
	v_mul_f32_e32 v9, v9, v9
	v_mul_f32_e32 v10, v10, v10
	v_cvt_pk_bf16_f32 v8, v12, v8
	v_cvt_pk_bf16_f32 v9, v9, v10
	v_cvt_pk_bf16_f32 v10, v19, v13
	v_mad_i64_i32 v[12:13], s[20:21], v18, s3, v[122:123]
	s_nop 0
	v_lshl_add_u64 v[12:13], v[12:13], 0, s[14:15]
	v_max_f32_e32 v11, 0, v11
	v_lshl_add_u64 v[12:13], v[12:13], 0, s[22:23]
	s_nop 0
	v_mul_f32_e32 v11, v11, v11
	v_lshl_add_u64 v[12:13], v[12:13], 0, v[16:17]
	v_max_f32_e32 v0, 0, v0
	v_max_f32_e32 v1, 0, v1
	v_max_f32_e32 v2, 0, v2
	v_cvt_pk_bf16_f32 v11, v14, v11
	global_store_dwordx4 v[12:13], v[8:11], off
	s_nop 0
	s_nop 0
	v_mul_f32_e32 v8, v0, v0
	v_max_f32_e32 v0, v5, v5
	v_mul_f32_e32 v5, v1, v1
	v_max_f32_e32 v1, v6, v6
	v_mul_f32_e32 v6, v2, v2
	v_max_f32_e32 v0, 0, v0
	v_max_f32_e32 v1, 0, v1
	v_max_f32_e32 v2, 0, v7
	v_max_f32_e32 v3, 0, v3
	v_max_f32_e32 v4, 0, v4
	v_mul_f32_e32 v0, v0, v0
	v_mul_f32_e32 v1, v1, v1
	v_mul_f32_e32 v2, v2, v2
	v_mul_f32_e32 v3, v3, v3
	s_and_b64 vcc, exec, s[6:7]
	s_mov_b32 s39, s2
	s_mov_b32 s40, s4
	s_mov_b64 s[20:21], s[12:13]
	s_mov_b64 s[14:15], s[10:11]
	v_mul_f32_e32 v4, v4, v4
	v_cvt_pk_bf16_f32 v0, v4, v0
	v_cvt_pk_bf16_f32 v1, v1, v2
	v_cvt_pk_bf16_f32 v2, v8, v5
	v_cvt_pk_bf16_f32 v3, v6, v3
	global_store_dwordx4 v[12:13], v[0:3], off offset:256
	s_cbranch_vccz .LBB0_3794
	s_branch .LBB0_3806
